# P0 adaLN: column blocks dealt XCD-contiguously so cache lines shared by neighbouring 48-column blocks are fetched into one L2
# speedup vs baseline: 1.0063x; 1.0053x over previous
; __global__ void __launch_bounds__(NTHR, 2) fwd_kernel(Args a) {
;     ...
;         for (int cb = bx; cb < 256; cb += G) {
;             const int col = cb * 48 + (lane < 48 ? lane : 47);
;             float acc[5] = {0.f, 0.f, 0.f, 0.f, 0.f};
;             const float* wp = a.in[I_WADA] + (size_t)(wave * 256) * MODW + col;
; #pragma unroll 16
;             for (int kk = 0; kk < 256; ++kk) {
;                 const float w = wp[(size_t)kk * MODW];
; #pragma unroll
;                 for (int r = 0; r < 5; ++r) acc[r] += w * sl[r * DM + wave * 256 + kk];
.LBB0_100:
	s_or_b64 exec, exec, s[0:1]
	s_add_u32 s68, s66, 0x10000
	s_addc_u32 s69, s67, 0
	s_cmpk_lt_i32 s88, 0x100
	s_cselect_b64 s[8:9], -1, 0
	s_cmpk_gt_i32 s88, 0xff
	s_waitcnt lgkmcnt(0)
	s_barrier
	s_cbranch_scc1 .LBB0_109
	v_and_b32_e32 v1, 63, v0
	v_cmp_gt_u32_e32 vcc, 48, v1
	s_mov_b32 s5, 0x2aaaaaab
	v_lshl_add_u32 v4, v1, 2, 0
	v_cndmask_b32_e32 v2, 47, v1, vcc
	v_mul_hi_i32 v1, v0, s5
	s_ashr_i32 s0, s12, 6
	v_lshrrev_b32_e32 v3, 31, v1
	v_ashrrev_i32_e32 v1, 3, v1
	s_lshl_b32 s2, s0, 10
	v_add_u32_e32 v3, v1, v3
	s_add_i32 s15, s2, 0
	s_movk_i32 s2, 0xf0
	v_mul_lo_u32 v1, v3, 48
	v_readlane_b32 s16, v254, 1
	s_lshl_b32 s1, s0, 8
	s_mul_i32 s4, s0, 0xc00000
	v_cmp_gt_i32_e64 s[2:3], s2, v0
	v_sub_u32_e32 v0, v0, v1
	s_mul_i32 s12, s0, 0x3c0
	s_movk_i32 s0, 0xc0
	v_readlane_b32 s24, v254, 9
	s_mul_hi_i32 s1, s1, 0xc000
	v_lshl_add_u32 v5, v0, 2, 0
	s_movk_i32 s5, 0x3000
	v_mul_lo_u32 v6, v3, s0
	v_readlane_b32 s17, v254, 2
	v_readlane_b32 s18, v254, 3
	v_readlane_b32 s19, v254, 4
	v_readlane_b32 s20, v254, 5
	v_readlane_b32 s21, v254, 6
	v_readlane_b32 s22, v254, 7
	v_readlane_b32 s23, v254, 8
	v_readlane_b32 s25, v254, 10
	v_readlane_b32 s26, v254, 11
	v_readlane_b32 s27, v254, 12
	v_readlane_b32 s28, v254, 13
	v_readlane_b32 s29, v254, 14
	v_readlane_b32 s30, v254, 15
	v_readlane_b32 s31, v254, 16
	s_add_u32 s0, s24, s4
	s_mov_b32 s14, 0xc000
	v_mul_lo_u32 v1, v3, s5
	s_addc_u32 s1, s25, s1
	s_and_b32 s98, s88, 7
	s_lshl_b32 s98, s98, 5
	s_lshr_b32 s99, s88, 3
	s_or_b32 s98, s98, s99
	v_mad_u64_u32 v[2:3], s[4:5], s98, 48, v[2:3]
	s_mul_i32 s16, s86, 48
	s_mov_b32 s17, 0x18000
	s_mov_b32 s18, 0x24000
	s_mov_b32 s19, 0x30000
	s_mov_b32 s20, 0x3c000
	s_mov_b32 s21, 0x48000
	s_mov_b32 s22, 0x54000
	s_mov_b32 s23, 0x60000
	s_mov_b32 s24, 0x6c000
	s_mov_b32 s25, 0x78000
	s_mov_b32 s26, 0x84000
	s_mov_b32 s27, 0x90000
	s_mov_b32 s28, 0x9c000
	s_mov_b32 s29, 0xa8000
	s_mov_b32 s30, 0xb4000
	v_add_u32_e32 v12, s12, v4
	v_add_u32_e32 v13, v5, v6
	s_mov_b32 s31, s98
	s_branch .LBB0_103
